# K-rotation also in ffn1 (256B per m-tile, wrap 2KB) on top of ffn2 krot
# speedup vs baseline: 1.0104x; 1.0039x over previous
.LBB0_187:
	s_lshr_b32 s15, s14, 5
	s_and_b32 s16, s15, 0x3fffff8
	s_and_b32 s15, s14, 7
	v_mov_b32_e32 v5, v254
	s_or_b32 s17, s16, s15
	s_lshl_b32 s26, s17, 7
	v_ashrrev_i32_e32 v0, 3, v5
	s_lshl_b32 s16, s16, 9
	s_lshl_b32 s17, s14, 4
	v_xor_b32_e32 v4, v0, v5
	s_sub_i32 s16, s17, s16
	v_lshlrev_b32_e32 v1, 3, v4
	s_and_b32 s20, s16, 0xffffff80
	v_and_b32_e32 v6, 56, v1
	v_ashrrev_i32_e32 v1, 31, v0
	s_ashr_i32 s21, s20, 31
	v_lshlrev_b64 v[2:3], 10, v[0:1]
	s_lshl_b64 s[22:23], s[20:21], 11
	s_mov_b64 s[16:17], -1
	s_and_b64 vcc, exec, s[36:37]
	v_lshlrev_b64 v[2:3], 1, v[2:3]
	v_lshlrev_b32_e32 v148, 1, v6
	v_lshlrev_b32_e32 v6, 4, v5
	s_cbranch_vccz .LBB0_189
	s_lshl_b64 s[16:17], s[26:27], 11
	s_add_u32 s16, s40, s16
	s_addc_u32 s17, s41, s17
	s_lshl_b32 s36, s26, 1
	s_and_b32 s36, s36, 0x700
	s_add_u32 s16, s16, s36
	s_addc_u32 s17, s17, 0
	v_lshlrev_b32_e32 v85, 4, v5
	v_lshl_add_u64 v[8:9], s[16:17], 0, v[2:3]
	v_readfirstlane_b32 s16, v85
	v_add_u32_e32 v7, 0x1000, v85
	v_lshl_add_u64 v[8:9], v[8:9], 0, v[148:149]
	s_mov_b32 m0, s16
	v_readfirstlane_b32 s16, v7
	v_add_u32_e32 v7, 0x2000, v85
	s_add_u32 s36, s25, s22
	s_barrier
	global_load_lds_dwordx4 v[8:9], off
	v_lshl_add_u64 v[12:13], v[8:9], 0, s[58:59]
	s_mov_b32 m0, s16
	v_readfirstlane_b32 s16, v7
	v_add_u32_e32 v7, 0x3000, v85
	s_addc_u32 s37, s33, s23
	s_lshl_b32 s17, s26, 1
	s_and_b32 s17, s17, 0x700
	s_add_u32 s36, s36, s17
	s_addc_u32 s37, s37, 0
	global_load_lds_dwordx4 v[12:13], off
	v_lshl_add_u64 v[12:13], v[8:9], 0, s[60:61]
	s_mov_b32 m0, s16
	v_readfirstlane_b32 s16, v7
	v_add_u32_e32 v7, 0x4000, v85
	v_lshl_add_u64 v[10:11], s[36:37], 0, v[2:3]
	global_load_lds_dwordx4 v[12:13], off
	v_lshl_add_u64 v[8:9], v[8:9], 0, s[62:63]
	s_mov_b32 m0, s16
	v_readfirstlane_b32 s16, v7
	v_add_u32_e32 v7, 0x5000, v85
	v_lshl_add_u64 v[10:11], v[10:11], 0, v[148:149]
	global_load_lds_dwordx4 v[8:9], off
	s_mov_b32 m0, s16
	v_readfirstlane_b32 s16, v7
	v_add_u32_e32 v7, 0x6000, v85
	global_load_lds_dwordx4 v[10:11], off
	v_lshl_add_u64 v[8:9], v[10:11], 0, s[58:59]
	s_mov_b32 m0, s16
	v_readfirstlane_b32 s16, v7
	v_add_u32_e32 v7, 0x7000, v85
	global_load_lds_dwordx4 v[8:9], off
	v_lshl_add_u64 v[8:9], v[10:11], 0, s[60:61]
	s_mov_b32 m0, s16
	v_readfirstlane_b32 s16, v7
	global_load_lds_dwordx4 v[8:9], off
	v_lshl_add_u64 v[8:9], v[10:11], 0, s[62:63]
	s_mov_b32 m0, s16
	s_mov_b64 s[16:17], 0
	global_load_lds_dwordx4 v[8:9], off

.LBB0_191:
	s_add_u32 s17, s40, s30
	s_addc_u32 s36, s41, s31
	s_and_b64 s[30:31], s[8:9], exec
	v_lshrrev_b32_e32 v7, 4, v5
	v_and_b32_e32 v9, 7, v5
	s_cselect_b32 s31, s36, 0
	s_cselect_b32 s30, s17, 0
	s_add_u32 s28, s25, s28
	v_bfe_u32 v8, v5, 4, 2
	v_bitop3_b32 v7, v7, v9, 3 bitop3:0x6c
	s_addc_u32 s29, s33, s29
	v_lshlrev_b32_e32 v86, 4, v7
	v_bitop3_b32 v7, v8, v9, 4 bitop3:0x36
	s_lshl_b32 s14, s14, 2
	v_and_b32_e32 v6, 15, v5
	v_lshlrev_b32_e32 v87, 4, v7
	v_lshrrev_b32_e32 v7, 1, v5
	s_and_b32 s14, s14, 0xfffffc00
	s_lshl_b32 s15, s15, 7
	v_and_or_b32 v6, v7, s47, v6
	s_or_b32 s14, s14, s15
	s_mov_b32 s15, s27
	v_lshlrev_b32_e32 v88, 7, v6
	v_lshl_add_u64 v[6:7], s[28:29], 0, v[148:149]
	v_lshl_add_u64 v[8:9], s[30:31], 0, v[148:149]
	v_lshlrev_b64 v[0:1], 11, v[0:1]
	s_lshl_b64 s[14:15], s[14:15], 11
	v_lshlrev_b32_e32 v4, 4, v4
	v_lshl_add_u64 v[64:65], v[8:9], 0, v[2:3]
	v_lshl_add_u64 v[66:67], v[6:7], 0, v[2:3]
	s_and_b32 s16, s46, 7
	s_lshl_b32 s16, s16, 8
	v_mov_b32_e32 v10, s16
	v_mov_b32_e32 v11, 0
	v_lshl_add_u64 v[64:65], v[64:65], 0, v[10:11]
	v_lshl_add_u64 v[66:67], v[66:67], 0, v[10:11]
	v_lshl_add_u64 v[2:3], v[0:1], 0, s[14:15]
	v_and_b32_e32 v148, 0x70, v4
	v_lshl_add_u64 v[0:1], v[0:1], 0, s[22:23]
	v_lshlrev_b32_e32 v5, 7, v5
	v_or_b32_e32 v2, v2, v148
	v_lshl_add_u64 v[0:1], v[0:1], 0, v[148:149]
	v_mov_b32_e32 v4, 0
	s_mov_b32 s16, 0
	v_and_b32_e32 v89, 0x2780, v5
	v_lshl_add_u64 v[68:69], v[64:65], 0, s[58:59]
	v_lshl_add_u64 v[70:71], v[64:65], 0, s[60:61]
	v_lshl_add_u64 v[72:73], v[64:65], 0, s[62:63]
	v_lshl_add_u64 v[74:75], v[66:67], 0, s[58:59]
	v_lshl_add_u64 v[76:77], v[66:67], 0, s[60:61]
	v_lshl_add_u64 v[78:79], v[66:67], 0, s[62:63]
	v_lshl_add_u64 v[80:81], s[10:11], 0, v[2:3]
	v_lshl_add_u64 v[82:83], s[10:11], 0, v[0:1]
	s_mov_b64 s[22:23], 0
	s_mov_b32 s17, 0
	v_mov_b32_e32 v5, v4
	v_mov_b32_e32 v6, v4
	v_mov_b32_e32 v7, v4
	v_mov_b32_e32 v12, v4
	v_mov_b32_e32 v13, v4
	v_mov_b32_e32 v14, v4
	v_mov_b32_e32 v15, v4
	v_mov_b32_e32 v0, v4
	v_mov_b32_e32 v1, v4
	v_mov_b32_e32 v2, v4
	v_mov_b32_e32 v3, v4
	v_mov_b32_e32 v8, v4
	v_mov_b32_e32 v9, v4
	v_mov_b32_e32 v10, v4
	v_mov_b32_e32 v11, v4
	v_mov_b32_e32 v16, v4
	v_mov_b32_e32 v17, v4
	v_mov_b32_e32 v18, v4
	v_mov_b32_e32 v19, v4
	v_mov_b32_e32 v20, v4
	v_mov_b32_e32 v21, v4
	v_mov_b32_e32 v22, v4
	v_mov_b32_e32 v23, v4
	v_mov_b32_e32 v24, v4
	v_mov_b32_e32 v25, v4
	v_mov_b32_e32 v26, v4
	v_mov_b32_e32 v27, v4
	v_mov_b32_e32 v28, v4
	v_mov_b32_e32 v29, v4
	v_mov_b32_e32 v30, v4
	v_mov_b32_e32 v31, v4
	v_mov_b32_e32 v32, v4
	v_mov_b32_e32 v33, v4
	v_mov_b32_e32 v34, v4
	v_mov_b32_e32 v35, v4
	v_mov_b32_e32 v36, v4
	v_mov_b32_e32 v37, v4
	v_mov_b32_e32 v38, v4
	v_mov_b32_e32 v39, v4
	s_waitcnt vmcnt(0)
	v_mov_b32_e32 v40, v4
	v_mov_b32_e32 v41, v4
	v_mov_b32_e32 v42, v4
	v_mov_b32_e32 v43, v4
	v_mov_b32_e32 v44, v4
	v_mov_b32_e32 v45, v4
	v_mov_b32_e32 v46, v4
	v_mov_b32_e32 v47, v4
	v_mov_b32_e32 v48, v4
	v_mov_b32_e32 v49, v4
	v_mov_b32_e32 v50, v4
	v_mov_b32_e32 v51, v4
	v_mov_b32_e32 v52, v4
	v_mov_b32_e32 v53, v4
	v_mov_b32_e32 v54, v4
	v_mov_b32_e32 v55, v4
	v_mov_b32_e32 v56, v4
	v_mov_b32_e32 v57, v4
	v_mov_b32_e32 v58, v4
	v_mov_b32_e32 v59, v4
	v_mov_b32_e32 v60, v4
	v_mov_b32_e32 v61, v4
	v_mov_b32_e32 v62, v4
	v_mov_b32_e32 v63, v4
	s_branch .LBB0_193

.LBB0_197:
	s_andn2_b64 vcc, exec, s[14:15]
	s_cbranch_vccnz .LBB0_192
	s_add_i32 s14, s16, 0x8000
	s_and_b32 s14, s14, 0x8000
	v_add_u32_e32 v94, s14, v85
	s_lshl_b32 s15, s26, 1
	s_and_b32 s15, s15, 0x700
	v_readfirstlane_b32 s14, v94
	s_mov_b32 m0, s14
	s_add_u32 s14, s15, s22
	s_add_u32 s14, s14, 0x80
	s_and_b32 s14, s14, 0x7ff
	s_add_u32 s14, s14, 0xe0c1000
	s_mov_b32 s15, 0
	v_lshl_add_u64 v[92:93], v[80:81], 0, s[14:15]
	s_sub_u32 s14, s14, 0xdec0000
	v_lshl_add_u64 v[90:91], v[82:83], 0, s[14:15]
	global_load_lds_dwordx4 v[92:93], off
	s_add_u32 m0, m0, 0x1000
	v_lshl_add_u64 v[92:93], v[92:93], 0, s[58:59]
	global_load_lds_dwordx4 v[92:93], off
	s_add_u32 m0, m0, 0x1000
	v_lshl_add_u64 v[92:93], v[92:93], 0, s[58:59]
	global_load_lds_dwordx4 v[92:93], off
	s_add_u32 m0, m0, 0x1000
	v_lshl_add_u64 v[92:93], v[92:93], 0, s[58:59]
	global_load_lds_dwordx4 v[92:93], off
	s_add_u32 m0, m0, 0x1000
	s_nop 0
	global_load_lds_dwordx4 v[90:91], off
	s_add_u32 m0, m0, 0x1000
	v_lshl_add_u64 v[90:91], v[90:91], 0, s[58:59]
	global_load_lds_dwordx4 v[90:91], off
	s_add_u32 m0, m0, 0x1000
	v_lshl_add_u64 v[90:91], v[90:91], 0, s[58:59]
	global_load_lds_dwordx4 v[90:91], off
	s_add_u32 m0, m0, 0x1000
	v_lshl_add_u64 v[90:91], v[90:91], 0, s[58:59]
	global_load_lds_dwordx4 v[90:91], off
	s_branch .LBB0_192
